# split barrier + GEMM-join wait + skip no-op steps + write-through stores with no L2 write-back in the barrier
# speedup vs baseline: 1.0129x; 1.0129x over previous
; __global__ void __launch_bounds__(NTHR, 2) dit_fwd(Args args) {
;     ...
;     for (int st = args.ph_lo; st < args.ph_hi; ++st) {
;     ...
;         if (l == DEPTH - 1 && sub == 11 && fuse) seam = false;
;         if (!MK_PER_PHASE && seam && st + 1 < args.ph_hi) xcd_barrier(bar);
.LBB0_772:
	s_cmp_eq_u32 s10, 3
	v_readlane_b32 s2, v254, 11
	s_cselect_b64 s[0:1], -1, 0
	s_cmp_eq_u32 s2, 11
	s_cselect_b64 s[2:3], -1, 0
	s_and_b64 s[0:1], s[2:3], s[0:1]
	v_readlane_b32 s2, v254, 4
	v_readlane_b32 s3, v254, 5
	s_and_b64 s[0:1], s[0:1], s[2:3]
	v_readlane_b32 s2, v254, 36
	s_xor_b64 s[0:1], s[0:1], -1
	v_readlane_b32 s3, v254, 37
	s_and_b64 s[2:3], s[0:1], s[2:3]
	s_add_i32 s88, s88, 1
	v_readlane_b32 vcc_lo, v253, 61
	s_nop 3
	s_cmp_eq_u32 vcc_lo, 0x100
	s_cbranch_scc1 .Lp3_fused
	s_mov_b32 vcc_lo, 0x800001e0
	s_mov_b32 vcc_hi, 0x7
	s_branch .Lp3_loop
.Lp3_fused:
	s_mov_b32 vcc_lo, 0x800001e0
	s_mov_b32 vcc_hi, 0x20117
.Lp3_loop:
	s_cmp_gt_u32 s88, 63
	s_cbranch_scc1 .Lp3_done
	s_bitcmp1_b64 vcc, s88
	s_cbranch_scc0 .Lp3_done
	s_add_i32 s88, s88, 1
	s_branch .Lp3_loop
.Lp3_done:
	s_cmp_ge_i32 s88, s89
	s_cselect_b64 s[0:1], -1, 0
	s_cmp_lt_i32 s88, s89
	s_cselect_b64 s[4:5], -1, 0
	s_and_b64 s[2:3], s[2:3], s[4:5]
	s_andn2_b64 vcc, exec, s[2:3]
	s_cbranch_vccz .LBB0_773
	s_getpc_b64 s[98:99]
